# sgu_unit: hoisted norm-gain loads into the main load batch and added next-unit cache prefetch
# baseline (speedup 1.0000x reference)
; #define LAS __attribute__((address_space(3)))
; __device__ __forceinline__ int fresh_tid() { int t = threadIdx.x; asm volatile("" : "+v"(t)); return t; }
; __device__ __forceinline__ void sgu_unit(int chunk, int g, const bf16_t* ZUV, const float* SS2, const float* gn, const bf16_t* SGUW, const float* bs, bf16_t* MIX, LAS unsigned char* lds) {
;     const int tid = fresh_tid(), lane = tid & 63, wid = __builtin_amdgcn_readfirstlane(tid >> 6), q32 = lane & 31, hi = lane >> 5;
;     LAS bf16_t* ZT = (LAS bf16_t*)lds;
;     const int r0 = chunk * 128;
;     const int tb = wid & 3, cb0 = (wid >> 2) * 2, t = 32 * tb + q32;
;     const int sr = tid & 127, qd = __builtin_amdgcn_readfirstlane(tid >> 7);
;     const bf16_t* zp = ZUV + (size_t)(r0 + sr) * 2048 + 1024 + g * 128 + qd * 32;
;     const bf16_t* wp = SGUW + (size_t)(g * 128 + t) * 128 + 8 * hi;
;     const bf16_t* zup = ZUV + (size_t)(r0 + t) * 2048 + g * 128;
;     u32x4 w[4]; f32x4 sq[4]; bf16x8 wvv[8]; u32x2 zav[4], zbv[4];
; #pragma unroll
;     for (int j = 0; j < 4; ++j) { w[j] = *(const u32x4*)(zp + j * 8); sq[j] = *(const f32x4*)(SS2 + (size_t)(r0 + sr) * 16 + 4 * j); }
; #pragma unroll
;     for (int ks = 0; ks < 8; ++ks) wvv[ks] = *(const bf16x8*)(wp + 16 * ks);
; #pragma unroll
;     for (int j = 0; j < 4; ++j) { zav[j] = *(const u32x2*)(zup + 32 * cb0 + 8 * j + 4 * hi); zbv[j] = *(const u32x2*)(zup + 32 * cb0 + 8 * j + 4 * hi + 32); }
;     const float bt = bs[g * 128 + t];
;     asm volatile("" : "+v"(w[0]), "+v"(w[1]), "+v"(w[2]), "+v"(w[3]), "+v"(sq[0]), "+v"(sq[1]), "+v"(sq[2]), "+v"(sq[3]),
;                  "+v"(wvv[0]), "+v"(wvv[1]), "+v"(wvv[2]), "+v"(wvv[3]), "+v"(wvv[4]), "+v"(wvv[5]), "+v"(wvv[6]), "+v"(wvv[7]),
;                  "+v"(zav[0]), "+v"(zav[1]), "+v"(zav[2]), "+v"(zav[3]), "+v"(zbv[0]), "+v"(zbv[1]), "+v"(zbv[2]), "+v"(zbv[3]) :: "memory");
.LBB0_248:
	s_or_b64 exec, exec, s[0:1]
	v_readlane_b32 s76, v253, 0
	v_readlane_b32 s77, v253, 1
	v_readlane_b32 s78, v253, 2
	v_readlane_b32 s79, v253, 3
	v_readlane_b32 s80, v253, 4
	v_readlane_b32 s81, v253, 5
	v_readlane_b32 s82, v253, 6
	v_readlane_b32 s83, v253, 7
	s_mov_b64 s[20:21], s[76:77]
	v_readlane_b32 s0, v254, 12
	s_mov_b64 s[22:23], s[78:79]
	v_readlane_b32 s76, v253, 12
	v_readlane_b32 s1, v254, 13
	v_readlane_b32 s90, v253, 26
	v_readlane_b32 s91, v253, 27
	v_readlane_b32 s12, v253, 32
	v_readlane_b32 s16, v253, 34
	s_andn2_b64 vcc, exec, s[0:1]
	v_readlane_b32 s8, v252, 8
	v_readlane_b32 s9, v252, 7
	s_mov_b32 s10, s2
	s_mov_b32 s98, 0x1000000
	s_mov_b32 s99, 0
	s_mov_b32 s100, 0x40000
	s_mov_b32 s101, 0
	s_mov_b64 s[14:15], s[90:91]
	v_readlane_b32 s13, v253, 33
	v_readlane_b32 s17, v253, 35
	v_readlane_b32 s20, v252, 9
	s_movk_i32 s21, 0x110
	s_waitcnt lgkmcnt(0)
	s_barrier
	v_readlane_b32 s77, v253, 13
	v_readlane_b32 s78, v253, 14
	v_readlane_b32 s79, v253, 15
	v_readlane_b32 s80, v253, 16
	v_readlane_b32 s81, v253, 17
	v_readlane_b32 s82, v253, 18
	v_readlane_b32 s83, v253, 19
	v_readlane_b32 s84, v253, 20
	v_readlane_b32 s85, v253, 21
	v_readlane_b32 s86, v253, 22
	v_readlane_b32 s87, v253, 23
	v_readlane_b32 s88, v253, 24
	v_readlane_b32 s89, v253, 25
	s_cbranch_vccnz .LBB0_250
.LBB0_249:
	v_mov_b32_e32 v0, v198
	v_mov_b32_e32 v2, s9
	v_readfirstlane_b32 s0, v0
	s_lshr_b32 s4, s0, 1
	v_and_b32_e32 v30, 31, v0
	s_and_b32 s4, s4, 0x60
	v_or_b32_e32 v6, s4, v30
	s_movk_i32 s4, 0x7f
	v_bfi_b32 v2, s4, v0, v2
	s_and_b32 s1, s9, 0xffffff80
	v_ashrrev_i32_e32 v3, 31, v2
	v_lshlrev_b64 v[4:5], 12, v[2:3]
	s_and_b32 s6, s8, 0x380
	s_ashr_i32 s0, s0, 2
	v_or_b32_e32 v80, s1, v6
	v_lshl_add_u64 v[4:5], s[54:55], 0, v[4:5]
	s_lshl_b32 s50, s6, 1
	s_and_b32 s4, s0, 0xffffffe0
	v_ashrrev_i32_e32 v81, 31, v80
	v_lshl_add_u64 v[4:5], v[4:5], 0, s[50:51]
	s_ashr_i32 s5, s4, 31
	v_or_b32_e32 v36, s6, v6
	v_lshlrev_b64 v[6:7], 12, v[80:81]
	v_lshl_add_u64 v[4:5], s[4:5], 1, v[4:5]
	v_lshl_add_u64 v[34:35], s[54:55], 0, v[6:7]
	v_lshlrev_b64 v[2:3], 6, v[2:3]
	s_andn2_b32 s0, s0, 63
	v_bfe_u32 v65, v0, 5, 1
	v_lshl_add_u64 v[2:3], s[16:17], 0, v[2:3]
	global_load_dwordx4 v[6:9], v[4:5], off offset:2096
	global_load_dwordx4 v[10:13], v[4:5], off offset:2080
	global_load_dwordx4 v[14:17], v[4:5], off offset:2064
	global_load_dwordx4 v[18:21], v[4:5], off offset:2048
	v_lshl_add_u64 v[238:239], v[4:5], 0, s[98:99]
	global_load_dwordx4 v[22:25], v[2:3], off offset:48
	global_load_dwordx4 v[26:29], v[2:3], off offset:32
	global_load_dwordx4 v[82:85], v[2:3], off offset:16
	global_load_dwordx4 v[86:89], v[2:3], off
	v_lshl_add_u64 v[240:241], v[2:3], 0, s[100:101]
	v_lshl_add_u64 v[4:5], v[34:35], 0, s[50:51]
	s_ashr_i32 s1, s0, 31
	v_and_b32_e32 v31, 0x7f, v0
	v_lshlrev_b32_e32 v0, 8, v36
	v_lshlrev_b32_e32 v32, 3, v65
	v_mov_b32_e32 v33, v1
	v_lshl_add_u64 v[4:5], s[0:1], 1, v[4:5]
	v_lshl_add_u64 v[2:3], s[12:13], 0, v[0:1]
	v_lshlrev_b32_e32 v0, 4, v65
	v_lshl_add_u64 v[4:5], v[4:5], 0, v[32:33]
	v_lshl_add_u64 v[2:3], v[2:3], 0, v[0:1]
	v_lshl_add_u64 v[242:243], v[4:5], 0, s[98:99]
	global_load_dwordx2 v[78:79], v[4:5], off
	global_load_dwordx2 v[76:77], v[4:5], off offset:64
	global_load_dwordx2 v[74:75], v[4:5], off offset:16
	global_load_dwordx2 v[72:73], v[4:5], off offset:80
	global_load_dwordx2 v[70:71], v[4:5], off offset:32
	global_load_dwordx2 v[68:69], v[4:5], off offset:96
	global_load_dwordx2 v[66:67], v[4:5], off offset:48
	global_load_dwordx2 v[62:63], v[4:5], off offset:112
	v_lshlrev_b32_e32 v4, 2, v36
	global_load_dword v64, v4, s[22:23]
	global_load_dwordx4 v[34:37], v[2:3], off offset:224
	global_load_dwordx4 v[38:41], v[2:3], off offset:192
	global_load_dwordx4 v[42:45], v[2:3], off offset:160
	global_load_dwordx4 v[46:49], v[2:3], off offset:128
	global_load_dwordx4 v[50:53], v[2:3], off offset:96
	global_load_dwordx4 v[54:57], v[2:3], off offset:64
	global_load_dwordx4 v[58:61], v[2:3], off offset:32
	s_nop 0
	global_load_dwordx4 v[2:5], v[2:3], off
	s_lshl_b32 s1, s6, 2
	s_add_u32 s1, s14, s1
	s_addc_u32 s11, s15, 0
	s_lshl_b64 s[6:7], s[4:5], 2
	s_add_u32 s6, s1, s6
	s_addc_u32 s7, s11, s7
	s_mul_i32 s1, s4, 0x110
	s_add_i32 s1, s1, 0
	v_lshl_add_u32 v31, v31, 1, s1
	s_add_i32 s10, s10, s34
	s_add_i32 s9, s9, s96
	s_add_i32 s8, s8, s20
	s_cmpk_gt_i32 s10, 0xfff
	global_load_dwordx4 v[206:209], v1, s[6:7]
	global_load_dwordx4 v[210:213], v1, s[6:7] offset:16
	global_load_dwordx4 v[214:217], v1, s[6:7] offset:32
	global_load_dwordx4 v[218:221], v1, s[6:7] offset:48
	global_load_dwordx4 v[222:225], v1, s[6:7] offset:64
	global_load_dwordx4 v[226:229], v1, s[6:7] offset:80
	global_load_dwordx4 v[230:233], v1, s[6:7] offset:96
	global_load_dwordx4 v[234:237], v1, s[6:7] offset:112
	s_waitcnt vmcnt(0)
; #define LAS __attribute__((address_space(3)))
; __device__ __forceinline__ unsigned pk_bf16(float lo, float hi) { const f32x2_t v = {lo, hi}; const bf16x2_t b = __builtin_convertvector(v, bf16x2_t); return __builtin_bit_cast(unsigned, b); }
; __device__ __forceinline__ float bf_lo(unsigned w) { return __uint_as_float(w << 16); }
; __device__ __forceinline__ float bf_hi(unsigned w) { return __uint_as_float(w & 0xffff0000u); }
; __device__ __forceinline__ void sgu_unit(int chunk, int g, const bf16_t* ZUV, const float* SS2, const float* gn, const bf16_t* SGUW, const float* bs, bf16_t* MIX, LAS unsigned char* lds) {
;     ...
;     {
;         const float sm = ((sq[0].x + sq[0].y) + (sq[0].z + sq[0].w)) + ((sq[1].x + sq[1].y) + (sq[1].z + sq[1].w)) + ((sq[2].x + sq[2].y) + (sq[2].z + sq[2].w)) + ((sq[3].x + sq[3].y) + (sq[3].z + sq[3].w));
;         const float rs = rsqrtf(sm * (1.0f / 1024.0f) + EPS);
; #pragma unroll
;         for (int j = 0; j < 4; ++j) {
;             const float* gp = gn + g * 128 + qd * 32 + j * 8; const f32x4 g0 = *(const f32x4*)gp, g1 = *(const f32x4*)(gp + 4);
;             const float v[8] = {bf_lo(w[j].x) * rs * g0.x, bf_hi(w[j].x) * rs * g0.y, bf_lo(w[j].y) * rs * g0.z, bf_hi(w[j].y) * rs * g0.w, bf_lo(w[j].z) * rs * g1.x, bf_hi(w[j].z) * rs * g1.y, bf_lo(w[j].w) * rs * g1.z, bf_hi(w[j].w) * rs * g1.w};
;             LAS bf16_t* zt = ZT + (qd * 32 + j * 8) * 136 + sr;
; #pragma unroll
;             for (int e = 0; e < 8; ++e) zt[e * 136] = (bf16_t)(pk_bf16(v[e], 0.f) & 0xffffu);
;         }
;     }
;     __syncthreads();
	global_load_dword v244, v[238:239], off offset:2048
	global_load_dword v245, v[240:241], off
	global_load_dword v246, v[242:243], off
	global_load_dword v247, v[242:243], off offset:64
	s_nop 0
	v_mov_b32_e32 v32, v87
	v_mov_b32_e32 v33, v88
	v_mov_b32_e32 v87, v89
	v_pk_add_f32 v[32:33], v[32:33], v[86:87]
	v_mov_b32_e32 v86, v83
	v_mov_b32_e32 v87, v84
	v_mov_b32_e32 v83, v85
	v_pk_add_f32 v[82:83], v[86:87], v[82:83]
	v_pk_add_f32 v[32:33], v[32:33], v[32:33] op_sel_hi:[0,1]
	v_pk_add_f32 v[82:83], v[82:83], v[82:83] op_sel_hi:[0,1]
	v_add_f32_e32 v27, v26, v27
	v_add_f32_e32 v29, v28, v29
	v_mov_b32_e32 v26, v22
	v_mov_b32_e32 v28, v23
	v_mov_b32_e32 v32, v24
	v_mov_b32_e32 v82, v25
	v_pk_add_f32 v[22:23], v[26:27], v[28:29]
	v_pk_add_f32 v[24:25], v[32:33], v[82:83]
	v_lshlrev_b32_e32 v33, 16, v18
	v_pk_add_f32 v[22:23], v[22:23], v[24:25]
	v_and_b32_e32 v18, 0xffff0000, v18
	v_add_f32_e32 v22, v22, v23
	v_fmamk_f32 v22, v22, 0x3a800000, v201
	v_cmp_gt_f32_e32 vcc, s57, v22
	v_mul_f32_e32 v23, 0x4b800000, v22
	s_nop 0
	v_cndmask_b32_e32 v22, v22, v23, vcc
	v_rsq_f32_e32 v22, v22
	s_nop 0
	v_mul_f32_e32 v23, 0x45800000, v22
	v_cndmask_b32_e32 v32, v22, v23, vcc
	v_mul_f32_e32 v33, v32, v33
	v_mul_f32_e32 v18, v32, v18
	v_mul_f32_e32 v33, v206, v33
	v_lshlrev_b32_e32 v86, 16, v19
	v_mul_f32_e32 v18, v207, v18
	v_mul_f32_e32 v86, v32, v86
	v_and_b32_e32 v19, 0xffff0000, v19
	v_mul_f32_e32 v86, v208, v86
	v_mul_f32_e32 v19, v32, v19
	v_lshlrev_b32_e32 v87, 16, v20
	v_and_b32_e32 v20, 0xffff0000, v20
	v_cvt_pk_bf16_f32 v18, v18, s0
	v_mul_f32_e32 v19, v209, v19
	v_mul_f32_e32 v87, v32, v87
	v_mul_f32_e32 v20, v32, v20
	ds_write_b16 v31, v18 offset:272
	v_cvt_pk_bf16_f32 v18, v86, s0
	v_mul_f32_e32 v82, v210, v87
	v_mul_f32_e32 v20, v211, v20
	v_lshlrev_b32_e32 v83, 16, v21
	ds_write_b16 v31, v18 offset:544
	v_cvt_pk_bf16_f32 v18, v19, s0
	v_mul_f32_e32 v83, v32, v83
	v_and_b32_e32 v21, 0xffff0000, v21
	ds_write_b16 v31, v18 offset:816
	v_cvt_pk_bf16_f32 v18, v82, s0
	v_mul_f32_e32 v83, v212, v83
	v_mul_f32_e32 v21, v32, v21
	ds_write_b16 v31, v18 offset:1088
	v_cvt_pk_bf16_f32 v18, v20, s0
	v_mul_f32_e32 v21, v213, v21
	ds_write_b16 v31, v18 offset:1360
	v_cvt_pk_bf16_f32 v18, v83, s0
	ds_write_b16 v31, v18 offset:1632
	v_cvt_pk_bf16_f32 v18, v21, s0
	ds_write_b16 v31, v18 offset:1904
	v_lshlrev_b32_e32 v18, 16, v14
	v_and_b32_e32 v14, 0xffff0000, v14
	v_mul_f32_e32 v14, v32, v14
	v_lshlrev_b32_e32 v19, 16, v15
	v_mul_f32_e32 v14, v215, v14
	v_mul_f32_e32 v19, v32, v19
	v_and_b32_e32 v15, 0xffff0000, v15
	v_mul_f32_e32 v19, v216, v19
	v_mul_f32_e32 v15, v32, v15
	v_lshlrev_b32_e32 v20, 16, v16
	v_cvt_pk_bf16_f32 v14, v14, s0
	v_mul_f32_e32 v15, v217, v15
	v_mul_f32_e32 v20, v32, v20
	v_and_b32_e32 v16, 0xffff0000, v16
	ds_write_b16 v31, v14 offset:2448
	v_cvt_pk_bf16_f32 v14, v19, s0
	v_mul_f32_e32 v20, v218, v20
	v_mul_f32_e32 v16, v32, v16
	v_lshlrev_b32_e32 v21, 16, v17
	ds_write_b16 v31, v14 offset:2720
	v_cvt_pk_bf16_f32 v14, v15, s0
	v_mul_f32_e32 v16, v219, v16
	v_mul_f32_e32 v21, v32, v21
	v_and_b32_e32 v17, 0xffff0000, v17
	ds_write_b16 v31, v14 offset:2992
	v_cvt_pk_bf16_f32 v14, v20, s0
	v_mul_f32_e32 v18, v32, v18
	v_mul_f32_e32 v21, v220, v21
	v_mul_f32_e32 v17, v32, v17
	ds_write_b16 v31, v14 offset:3264
	v_cvt_pk_bf16_f32 v14, v16, s0
	v_mul_f32_e32 v18, v214, v18
	v_mul_f32_e32 v17, v221, v17
	ds_write_b16 v31, v14 offset:3536
	v_cvt_pk_bf16_f32 v14, v21, s0
	v_cvt_pk_bf16_f32 v33, v33, s0
	v_cvt_pk_bf16_f32 v18, v18, s0
	ds_write_b16 v31, v14 offset:3808
	v_cvt_pk_bf16_f32 v14, v17, s0
	ds_write_b16 v31, v33
	ds_write_b16 v31, v18 offset:2176
	ds_write_b16 v31, v14 offset:4080
	v_lshlrev_b32_e32 v33, 16, v10
	v_and_b32_e32 v10, 0xffff0000, v10
	v_mul_f32_e32 v10, v32, v10
	v_mul_f32_e32 v33, v32, v33
	s_waitcnt vmcnt(0)
	v_mul_f32_e32 v10, v10, v223
	v_lshlrev_b32_e32 v27, 16, v11
	v_mul_f32_e32 v27, v32, v27
	v_and_b32_e32 v11, 0xffff0000, v11
	v_mul_f32_e32 v27, v27, v224
	v_mul_f32_e32 v11, v32, v11
	v_lshlrev_b32_e32 v28, 16, v12
	v_and_b32_e32 v12, 0xffff0000, v12
	v_cvt_pk_bf16_f32 v10, v10, s0
	v_mul_f32_e32 v11, v11, v225
	v_mul_f32_e32 v28, v32, v28
	v_mul_f32_e32 v12, v32, v12
	ds_write_b16 v31, v10 offset:4624
	v_cvt_pk_bf16_f32 v10, v27, s0
	v_mul_f32_e32 v22, v28, v226
	v_mul_f32_e32 v12, v12, v227
	v_lshlrev_b32_e32 v23, 16, v13
	ds_write_b16 v31, v10 offset:4896
	v_cvt_pk_bf16_f32 v10, v11, s0
	v_mul_f32_e32 v23, v32, v23
	v_and_b32_e32 v13, 0xffff0000, v13
	ds_write_b16 v31, v10 offset:5168
	v_cvt_pk_bf16_f32 v10, v22, s0
	v_mul_f32_e32 v23, v23, v228
	v_mul_f32_e32 v13, v32, v13
	ds_write_b16 v31, v10 offset:5440
	v_cvt_pk_bf16_f32 v10, v12, s0
	v_mul_f32_e32 v13, v13, v229
	ds_write_b16 v31, v10 offset:5712
	v_cvt_pk_bf16_f32 v10, v23, s0
	ds_write_b16 v31, v10 offset:5984
	v_cvt_pk_bf16_f32 v10, v13, s0
	ds_write_b16 v31, v10 offset:6256
	v_lshlrev_b32_e32 v10, 16, v6
	v_and_b32_e32 v6, 0xffff0000, v6
	v_mul_f32_e32 v6, v32, v6
	v_lshlrev_b32_e32 v11, 16, v7
	v_mul_f32_e32 v6, v6, v231
	v_mul_f32_e32 v11, v32, v11
	v_and_b32_e32 v7, 0xffff0000, v7
	v_mul_f32_e32 v11, v11, v232
	v_mul_f32_e32 v7, v32, v7
	v_lshlrev_b32_e32 v12, 16, v8
	v_cvt_pk_bf16_f32 v6, v6, s0
	v_mul_f32_e32 v7, v7, v233
	v_mul_f32_e32 v12, v32, v12
	v_and_b32_e32 v8, 0xffff0000, v8
	ds_write_b16 v31, v6 offset:6800
	v_cvt_pk_bf16_f32 v6, v11, s0
	v_mul_f32_e32 v12, v12, v234
	v_mul_f32_e32 v8, v32, v8
	v_lshlrev_b32_e32 v13, 16, v9
	ds_write_b16 v31, v6 offset:7072
	v_cvt_pk_bf16_f32 v6, v7, s0
	v_mul_f32_e32 v8, v8, v235
	v_mul_f32_e32 v13, v32, v13
	v_and_b32_e32 v9, 0xffff0000, v9
	ds_write_b16 v31, v6 offset:7344
	v_cvt_pk_bf16_f32 v6, v12, s0
	v_mul_f32_e32 v13, v13, v236
	v_mul_f32_e32 v9, v32, v9
	ds_write_b16 v31, v6 offset:7616
	v_cvt_pk_bf16_f32 v6, v8, s0
	v_mul_f32_e32 v9, v9, v237
	ds_write_b16 v31, v6 offset:7888
	v_cvt_pk_bf16_f32 v6, v13, s0
	ds_write_b16 v31, v6 offset:8160
	v_cvt_pk_bf16_f32 v6, v9, s0
	v_mul_f32_e32 v10, v32, v10
	ds_write_b16 v31, v6 offset:8432
	v_or_b32_e32 v6, s0, v30
	v_mul_f32_e32 v26, v33, v222
	v_mul_f32_e32 v10, v10, v230
	v_mul_lo_u32 v6, v6, s21
	v_cvt_pk_bf16_f32 v24, v26, s0
	v_cvt_pk_bf16_f32 v10, v10, s0
	v_add3_u32 v0, 0, v6, v0
	ds_write_b16 v31, v24 offset:4352
	ds_write_b16 v31, v10 offset:6528
	s_waitcnt lgkmcnt(0)
	s_barrier
; #define LAS __attribute__((address_space(3)))
; __device__ __forceinline__ unsigned pk_bf16(float lo, float hi) { const f32x2_t v = {lo, hi}; const bf16x2_t b = __builtin_convertvector(v, bf16x2_t); return __builtin_bit_cast(unsigned, b); }
; __device__ __forceinline__ float bf_lo(unsigned w) { return __uint_as_float(w << 16); }
; __device__ __forceinline__ float bf_hi(unsigned w) { return __uint_as_float(w & 0xffff0000u); }
; __device__ __forceinline__ void sgu_unit(int chunk, int g, const bf16_t* ZUV, const float* SS2, const float* gn, const bf16_t* SGUW, const float* bs, bf16_t* MIX, LAS unsigned char* lds) {
;     ...
;     f32x16 d0, d1;
; #pragma unroll
;     for (int r = 0; r < 16; ++r) { d0[r] = 0.f; d1[r] = 0.f; }
; #pragma unroll
;     for (int ks = 0; ks < 8; ++ks) {
;         const bf16x8 z0 = *(const LAS bf16x8*)(ZT + (32 * cb0 + q32) * 136 + 16 * ks + 8 * hi);
;         const bf16x8 z1 = *(const LAS bf16x8*)(ZT + (32 * (cb0 + 1) + q32) * 136 + 16 * ks + 8 * hi);
;         d0 = __builtin_amdgcn_mfma_f32_32x32x16_bf16(z0, wvv[ks], d0, 0, 0, 0);
;         d1 = __builtin_amdgcn_mfma_f32_32x32x16_bf16(z1, wvv[ks], d1, 0, 0, 0);
;     }
;     bf16_t* op = MIX + (size_t)(r0 + t) * DM + g * 128;
; #pragma unroll
;     for (int j = 0; j < 4; ++j) {
;         const int c0 = 32 * cb0 + 8 * j + 4 * hi, c1 = c0 + 32;
;         const u32x2 za = zav[j], zb = zbv[j];
;         u32x2 wa, wb;
;         wa.x = pk_bf16(bf_lo(za.x) * (d0[4 * j + 0] + bt), bf_hi(za.x) * (d0[4 * j + 1] + bt)); wa.y = pk_bf16(bf_lo(za.y) * (d0[4 * j + 2] + bt), bf_hi(za.y) * (d0[4 * j + 3] + bt));
;         wb.x = pk_bf16(bf_lo(zb.x) * (d1[4 * j + 0] + bt), bf_hi(zb.x) * (d1[4 * j + 1] + bt)); wb.y = pk_bf16(bf_lo(zb.y) * (d1[4 * j + 2] + bt), bf_hi(zb.y) * (d1[4 * j + 3] + bt));
;         *(u32x2*)(op + c0) = wa; *(u32x2*)(op + c1) = wb;
;     }
;     __syncthreads();
	ds_read_b128 v[6:9], v0 offset:8704
	ds_read_b128 v[10:13], v0
	ds_read_b128 v[82:85], v0 offset:32
	s_waitcnt lgkmcnt(1)
	v_mfma_f32_32x32x16_bf16 v[18:33], v[10:13], v[2:5], 0
	ds_read_b128 v[86:89], v0 offset:8736
	v_mfma_f32_32x32x16_bf16 v[2:17], v[6:9], v[2:5], 0
	s_waitcnt lgkmcnt(1)
	v_mfma_f32_32x32x16_bf16 v[18:33], v[82:85], v[58:61], v[18:33]
	s_waitcnt lgkmcnt(0)
	v_mfma_f32_32x32x16_bf16 v[2:17], v[86:89], v[58:61], v[2:17]
	ds_read_b128 v[58:61], v0 offset:64
	ds_read_b128 v[82:85], v0 offset:8768
	s_waitcnt lgkmcnt(1)
	v_mfma_f32_32x32x16_bf16 v[18:33], v[58:61], v[54:57], v[18:33]
	s_waitcnt lgkmcnt(0)
	v_mfma_f32_32x32x16_bf16 v[2:17], v[82:85], v[54:57], v[2:17]
	ds_read_b128 v[54:57], v0 offset:96
	ds_read_b128 v[58:61], v0 offset:8800
	s_waitcnt lgkmcnt(1)
	v_mfma_f32_32x32x16_bf16 v[18:33], v[54:57], v[50:53], v[18:33]
	s_waitcnt lgkmcnt(0)
	v_mfma_f32_32x32x16_bf16 v[2:17], v[58:61], v[50:53], v[2:17]
	ds_read_b128 v[50:53], v0 offset:128
	ds_read_b128 v[54:57], v0 offset:8832
	s_waitcnt lgkmcnt(1)
	v_mfma_f32_32x32x16_bf16 v[18:33], v[50:53], v[46:49], v[18:33]
	s_waitcnt lgkmcnt(0)
	v_mfma_f32_32x32x16_bf16 v[2:17], v[54:57], v[46:49], v[2:17]
	ds_read_b128 v[46:49], v0 offset:160
	ds_read_b128 v[50:53], v0 offset:8864
	s_waitcnt lgkmcnt(1)
	v_mfma_f32_32x32x16_bf16 v[18:33], v[46:49], v[42:45], v[18:33]
	s_waitcnt lgkmcnt(0)
	v_mfma_f32_32x32x16_bf16 v[2:17], v[50:53], v[42:45], v[2:17]
	ds_read_b128 v[42:45], v0 offset:192
	ds_read_b128 v[46:49], v0 offset:8896
	s_waitcnt lgkmcnt(1)
	v_mfma_f32_32x32x16_bf16 v[18:33], v[42:45], v[38:41], v[18:33]
	s_waitcnt lgkmcnt(0)
	v_mfma_f32_32x32x16_bf16 v[2:17], v[46:49], v[38:41], v[2:17]
	ds_read_b128 v[38:41], v0 offset:224
	ds_read_b128 v[42:45], v0 offset:8928
	s_waitcnt lgkmcnt(1)
	v_mfma_f32_32x32x16_bf16 v[18:33], v[38:41], v[34:37], v[18:33]
	v_lshlrev_b32_e32 v38, 16, v78
	v_and_b32_e32 v39, 0xffff0000, v78
	s_waitcnt lgkmcnt(0)
	v_mfma_f32_32x32x16_bf16 v[2:17], v[42:45], v[34:37], v[2:17]
	s_nop 7
	v_add_f32_e64 v18, v64, v18
	v_add_f32_e64 v19, v64, v19
	v_mul_f32_e64 v18, v18, v38
	v_mul_f32_e64 v19, v19, v39
	v_lshlrev_b32_e32 v38, 16, v79
	v_and_b32_e32 v39, 0xffff0000, v79
	v_pk_add_f32 v[20:21], v[64:65], v[20:21] op_sel_hi:[0,1]
	v_pk_mul_f32 v[20:21], v[20:21], v[38:39]
	v_lshlrev_b64 v[34:35], 11, v[80:81]
	v_cvt_pk_bf16_f32 v18, v18, v19
	v_cvt_pk_bf16_f32 v19, v20, v21
	v_lshlrev_b32_e32 v20, 16, v76
	v_and_b32_e32 v21, 0xffff0000, v76
	v_pk_add_f32 v[2:3], v[64:65], v[2:3] op_sel_hi:[0,1]
	v_lshl_add_u64 v[34:35], s[52:53], 0, v[34:35]
	v_lshl_or_b32 v36, v65, 2, s0
	v_pk_mul_f32 v[2:3], v[2:3], v[20:21]
	v_lshlrev_b32_e32 v20, 16, v77
	v_and_b32_e32 v21, 0xffff0000, v77
	v_pk_add_f32 v[4:5], v[64:65], v[4:5] op_sel_hi:[0,1]
	v_lshl_add_u64 v[34:35], v[34:35], 0, s[50:51]
	v_pk_mul_f32 v[4:5], v[4:5], v[20:21]
	v_ashrrev_i32_e32 v37, 31, v36
	v_cvt_pk_bf16_f32 v2, v2, v3
	v_cvt_pk_bf16_f32 v3, v4, v5
	v_lshl_add_u64 v[4:5], v[36:37], 1, v[34:35]
	global_store_dwordx2 v[4:5], v[18:19], off
	global_store_dwordx2 v[4:5], v[2:3], off offset:64
	v_lshlrev_b32_e32 v2, 16, v74
	v_and_b32_e32 v3, 0xffff0000, v74
	v_pk_add_f32 v[18:19], v[64:65], v[22:23] op_sel_hi:[0,1]
	v_pk_mul_f32 v[2:3], v[18:19], v[2:3]
	v_lshlrev_b32_e32 v18, 16, v75
	v_and_b32_e32 v19, 0xffff0000, v75
	v_pk_add_f32 v[20:21], v[64:65], v[24:25] op_sel_hi:[0,1]
	v_pk_mul_f32 v[18:19], v[20:21], v[18:19]
	v_cvt_pk_bf16_f32 v2, v2, v3
	v_cvt_pk_bf16_f32 v3, v18, v19
	v_lshlrev_b32_e32 v18, 16, v72
	v_and_b32_e32 v19, 0xffff0000, v72
	v_pk_add_f32 v[6:7], v[64:65], v[6:7] op_sel_hi:[0,1]
	v_pk_mul_f32 v[6:7], v[6:7], v[18:19]
	v_lshlrev_b32_e32 v18, 16, v73
	v_and_b32_e32 v19, 0xffff0000, v73
	v_pk_add_f32 v[8:9], v[64:65], v[8:9] op_sel_hi:[0,1]
	v_pk_mul_f32 v[8:9], v[8:9], v[18:19]
	v_cvt_pk_bf16_f32 v6, v6, v7
	v_cvt_pk_bf16_f32 v7, v8, v9
	global_store_dwordx2 v[4:5], v[2:3], off offset:16
	global_store_dwordx2 v[4:5], v[6:7], off offset:80
	v_lshlrev_b32_e32 v2, 16, v70
	v_and_b32_e32 v3, 0xffff0000, v70
	v_pk_add_f32 v[6:7], v[64:65], v[26:27] op_sel_hi:[0,1]
	v_pk_mul_f32 v[2:3], v[6:7], v[2:3]
	v_lshlrev_b32_e32 v6, 16, v71
	v_and_b32_e32 v7, 0xffff0000, v71
	v_pk_add_f32 v[8:9], v[64:65], v[28:29] op_sel_hi:[0,1]
	v_pk_mul_f32 v[6:7], v[8:9], v[6:7]
	v_cvt_pk_bf16_f32 v2, v2, v3
	v_cvt_pk_bf16_f32 v3, v6, v7
	v_lshlrev_b32_e32 v6, 16, v68
	v_and_b32_e32 v7, 0xffff0000, v68
	v_pk_add_f32 v[8:9], v[64:65], v[10:11] op_sel_hi:[0,1]
	v_pk_mul_f32 v[6:7], v[8:9], v[6:7]
	v_lshlrev_b32_e32 v8, 16, v69
	v_and_b32_e32 v9, 0xffff0000, v69
	v_pk_add_f32 v[10:11], v[64:65], v[12:13] op_sel_hi:[0,1]
	v_pk_mul_f32 v[8:9], v[10:11], v[8:9]
	v_cvt_pk_bf16_f32 v6, v6, v7
	v_cvt_pk_bf16_f32 v7, v8, v9
	global_store_dwordx2 v[4:5], v[2:3], off offset:32
	global_store_dwordx2 v[4:5], v[6:7], off offset:96
	v_lshlrev_b32_e32 v2, 16, v66
	v_and_b32_e32 v3, 0xffff0000, v66
	v_pk_add_f32 v[6:7], v[64:65], v[30:31] op_sel_hi:[0,1]
	v_pk_mul_f32 v[2:3], v[6:7], v[2:3]
	v_lshlrev_b32_e32 v6, 16, v67
	v_and_b32_e32 v7, 0xffff0000, v67
	v_pk_add_f32 v[8:9], v[64:65], v[32:33] op_sel_hi:[0,1]
	v_pk_mul_f32 v[6:7], v[8:9], v[6:7]
	v_cvt_pk_bf16_f32 v2, v2, v3
	v_cvt_pk_bf16_f32 v3, v6, v7
	v_lshlrev_b32_e32 v6, 16, v62
	v_and_b32_e32 v7, 0xffff0000, v62
	v_pk_add_f32 v[8:9], v[64:65], v[14:15] op_sel_hi:[0,1]
	v_pk_mul_f32 v[6:7], v[8:9], v[6:7]
	v_lshlrev_b32_e32 v8, 16, v63
	v_and_b32_e32 v9, 0xffff0000, v63
	v_pk_add_f32 v[10:11], v[64:65], v[16:17] op_sel_hi:[0,1]
	v_pk_mul_f32 v[8:9], v[10:11], v[8:9]
	v_cvt_pk_bf16_f32 v6, v6, v7
	v_cvt_pk_bf16_f32 v7, v8, v9
	global_store_dwordx2 v[4:5], v[2:3], off offset:48
	global_store_dwordx2 v[4:5], v[6:7], off offset:112
	s_barrier
	s_cbranch_scc0 .LBB0_249
